# plus last-layer gate phase sample tile with all fragment loads in flight
# speedup vs baseline: 1.0073x; 1.0041x over previous
; #define LAS __attribute__((address_space(3)))
; #define SGT_LOAD(S_, KS_) do { _Pragma("unroll") for (int u = 0; u < U; ++u) { a0[S_][u] = *(const bf16x8*)(ap + (KS_) + 32 * u); if (MB == 2) a1[S_][u] = *(const bf16x8*)(ap + (size_t)16 * lda + (KS_) + 32 * u); \
;         _Pragma("unroll") for (int n = 0; n < NBW; ++n) b[S_][u][n] = *(const bf16x8*)(bp + (size_t)n * 16 * K + (KS_) + 32 * u); } } while (0)
; #define SGT_MMA(S_) do { _Pragma("unroll") for (int u = 0; u < U; ++u) _Pragma("unroll") for (int n = 0; n < NBW; ++n) { acc[0][n] = __builtin_amdgcn_mfma_f32_16x16x32_bf16(b[S_][u][n], a0[S_][u], acc[0][n], 0, 0, 0); \
;         if (MB == 2) acc[MB - 1][n] = __builtin_amdgcn_mfma_f32_16x16x32_bf16(b[S_][u][n], a1[S_][u], acc[MB - 1][n], 0, 0, 0); } } while (0)
;     ...
;     const bf16* ap = A + (size_t)(row0 + fr) * lda + k0 + 8 * fq;
;     const bf16* bp = Bt + (size_t)(col0 + wn * (TN / WN) + fr) * K + k0 + 8 * fq;
;     bf16x8 a0[2][U], a1[2][U], b[2][U][NBW];
;     ...
;     constexpr bool ONEPASS = 16 * MB * (TN / 4) <= NWAVES * 64;
;     typename F::Pre pre{};
;     if constexpr (ONEPASS) { if (tid < 16 * MB * (TN / 4)) pre = f.prefetch(tid / (TN / 4), 4 * (tid % (TN / 4))); }
;     SGT_LOAD(0, 0);
; #pragma unroll 1
;     for (int ks = 0; ks < KPER; ks += 64 * U) {
;         if (ks + 32 * U < KPER) SGT_LOAD(1, ks + 32 * U);
;         SGT_MMA(0);
;         if (ks + 64 * U < KPER) SGT_LOAD(0, ks + 64 * U);
;         if (ks + 32 * U < KPER) SGT_MMA(1);
;     }
;     ...
;     if constexpr (PREBAR) { asm volatile("s_waitcnt vmcnt(0)" ::: "memory"); __syncthreads(); }
;     LAS float* red = (LAS float*)lds;
; #pragma unroll
;     for (int m = 0; m < MB; ++m)
; #pragma unroll
;         for (int n = 0; n < NBW; ++n) *(LAS f32x4*)(red + (size_t)((wk * 16 * MB + 16 * m + fr) * P + wn * (TN / WN) + 16 * n + 4 * fq)) = acc[m][n];
;     __syncthreads();
.LBB0_1950:
	s_or_b64 exec, exec, s[16:17]
	s_ashr_i32 s7, s7, 6
	s_lshl_b32 s8, s7, 8
	v_or_b32_e32 v28, s6, v30
	v_lshlrev_b32_e32 v28, 11, v28
	v_add3_u32 v28, v28, s8, v2
	v_or_b32_e32 v29, s84, v30
	v_lshlrev_b32_e32 v29, 11, v29
	v_add3_u32 v29, v29, s8, v2
	s_mov_b64 s[44:45], s[90:91]
	s_add_u32 s46, s90, 0x8000
	s_addc_u32 s47, s91, 0
	s_add_u32 s50, s90, 0x10000
	s_addc_u32 s51, s91, 0
	s_add_u32 s52, s90, 0x18000
	s_addc_u32 s53, s91, 0
	s_mov_b64 s[18:19], s[30:31]
	s_add_u32 s24, s30, 0x8000
	s_addc_u32 s25, s31, 0
	global_load_dwordx4 v[32:35], v28, s[18:19]
	global_load_dwordx4 v[48:51], v28, s[24:25]
	global_load_dwordx4 v[116:119], v29, s[44:45]
	global_load_dwordx4 v[120:123], v29, s[46:47]
	global_load_dwordx4 v[124:127], v29, s[50:51]
	global_load_dwordx4 v[128:131], v29, s[52:53]
	global_load_dwordx4 v[36:39], v28, s[18:19] offset:64
	global_load_dwordx4 v[52:55], v28, s[24:25] offset:64
	global_load_dwordx4 v[132:135], v29, s[44:45] offset:64
	global_load_dwordx4 v[136:139], v29, s[46:47] offset:64
	global_load_dwordx4 v[140:143], v29, s[50:51] offset:64
	global_load_dwordx4 v[176:179], v29, s[52:53] offset:64
	global_load_dwordx4 v[40:43], v28, s[18:19] offset:128
	global_load_dwordx4 v[56:59], v28, s[24:25] offset:128
	global_load_dwordx4 v[182:185], v29, s[44:45] offset:128
	global_load_dwordx4 v[186:189], v29, s[46:47] offset:128
	global_load_dwordx4 v[190:193], v29, s[50:51] offset:128
	global_load_dwordx4 v[194:197], v29, s[52:53] offset:128
	global_load_dwordx4 v[44:47], v28, s[18:19] offset:192
	global_load_dwordx4 v[60:63], v28, s[24:25] offset:192
	global_load_dwordx4 v[198:201], v29, s[44:45] offset:192
	global_load_dwordx4 v[202:205], v29, s[46:47] offset:192
	global_load_dwordx4 v[206:209], v29, s[50:51] offset:192
	global_load_dwordx4 v[212:215], v29, s[52:53] offset:192
	v_lshl_or_b32 v217, s7, 5, v30
	s_movk_i32 s7, 0x110
	v_mad_u32_u24 v216, v217, s7, v22
	s_waitcnt vmcnt(18)
	v_mfma_f32_16x16x32_bf16 v[64:67], v[116:119], v[32:35], 0
	v_mfma_f32_16x16x32_bf16 v[80:83], v[116:119], v[48:51], 0
	v_mfma_f32_16x16x32_bf16 v[68:71], v[120:123], v[32:35], 0
	v_mfma_f32_16x16x32_bf16 v[84:87], v[120:123], v[48:51], 0
	v_mfma_f32_16x16x32_bf16 v[72:75], v[124:127], v[32:35], 0
	v_mfma_f32_16x16x32_bf16 v[108:111], v[124:127], v[48:51], 0
	v_mfma_f32_16x16x32_bf16 v[76:79], v[128:131], v[32:35], 0
	v_mfma_f32_16x16x32_bf16 v[112:115], v[128:131], v[48:51], 0
	s_waitcnt vmcnt(12)
	v_mfma_f32_16x16x32_bf16 v[64:67], v[132:135], v[36:39], v[64:67]
	v_mfma_f32_16x16x32_bf16 v[80:83], v[132:135], v[52:55], v[80:83]
	v_mfma_f32_16x16x32_bf16 v[68:71], v[136:139], v[36:39], v[68:71]
	v_mfma_f32_16x16x32_bf16 v[84:87], v[136:139], v[52:55], v[84:87]
	v_mfma_f32_16x16x32_bf16 v[72:75], v[140:143], v[36:39], v[72:75]
	v_mfma_f32_16x16x32_bf16 v[108:111], v[140:143], v[52:55], v[108:111]
	v_mfma_f32_16x16x32_bf16 v[76:79], v[176:179], v[36:39], v[76:79]
	v_mfma_f32_16x16x32_bf16 v[112:115], v[176:179], v[52:55], v[112:115]
	s_waitcnt vmcnt(6)
	v_mfma_f32_16x16x32_bf16 v[64:67], v[182:185], v[40:43], v[64:67]
	v_mfma_f32_16x16x32_bf16 v[80:83], v[182:185], v[56:59], v[80:83]
	v_mfma_f32_16x16x32_bf16 v[68:71], v[186:189], v[40:43], v[68:71]
	v_mfma_f32_16x16x32_bf16 v[84:87], v[186:189], v[56:59], v[84:87]
	v_mfma_f32_16x16x32_bf16 v[72:75], v[190:193], v[40:43], v[72:75]
	v_mfma_f32_16x16x32_bf16 v[108:111], v[190:193], v[56:59], v[108:111]
	v_mfma_f32_16x16x32_bf16 v[76:79], v[194:197], v[40:43], v[76:79]
	v_mfma_f32_16x16x32_bf16 v[112:115], v[194:197], v[56:59], v[112:115]
	s_waitcnt vmcnt(0)
	s_waitcnt lgkmcnt(0)
	s_barrier
	v_mfma_f32_16x16x32_bf16 v[64:67], v[198:201], v[44:47], v[64:67]
	v_mfma_f32_16x16x32_bf16 v[80:83], v[198:201], v[60:63], v[80:83]
	v_mfma_f32_16x16x32_bf16 v[68:71], v[202:205], v[44:47], v[68:71]
	v_mfma_f32_16x16x32_bf16 v[84:87], v[202:205], v[60:63], v[84:87]
	v_mfma_f32_16x16x32_bf16 v[72:75], v[206:209], v[44:47], v[72:75]
	v_mfma_f32_16x16x32_bf16 v[108:111], v[206:209], v[60:63], v[108:111]
	v_mfma_f32_16x16x32_bf16 v[76:79], v[212:215], v[44:47], v[76:79]
	v_mfma_f32_16x16x32_bf16 v[112:115], v[212:215], v[60:63], v[112:115]
	s_nop 1
	ds_write_b128 v216, v[64:67]
	ds_write_b128 v216, v[80:83] offset:4352
	ds_write_b128 v216, v[68:71] offset:64
	ds_write_b128 v216, v[84:87] offset:4416
	ds_write_b128 v216, v[72:75] offset:128
	ds_write_b128 v216, v[108:111] offset:4480
	ds_write_b128 v216, v[76:79] offset:192
	ds_write_b128 v216, v[112:115] offset:4544
	s_waitcnt lgkmcnt(0)
	s_barrier
	s_and_saveexec_b64 s[18:19], vcc
	s_cbranch_execz .LBB0_1947
	v_add_f32_e32 v4, v4, v5
	v_add_f32_e32 v5, v6, v7
	v_add_f32_e32 v4, v4, v5
	v_add_f32_e32 v5, v8, v9
	v_add_f32_e32 v6, v10, v11
	v_add_f32_e32 v5, v5, v6
	v_add_f32_e32 v4, v4, v5
	v_add_f32_e32 v5, v12, v13
	v_add_f32_e32 v6, v14, v15
	v_add_f32_e32 v5, v5, v6
	v_add_f32_e32 v4, v4, v5
	v_add_f32_e32 v5, v16, v17
	v_add_f32_e32 v6, v18, v19
	v_add_f32_e32 v5, v5, v6
	v_add_f32_e32 v4, v4, v5
	v_fmamk_f32 v4, v4, 0x3a800000, v1
	s_lshl_b32 s7, s84, 1
	v_rsq_f32_e32 v12, v4
	s_add_u32 s20, s14, s7
	s_addc_u32 s21, s15, 0
	s_lshr_b32 s7, s84, 4
	s_add_u32 s22, s10, s7
	v_lshlrev_b32_e32 v28, 16, v26
	v_and_b32_e32 v29, 0xffff0000, v26
	v_lshlrev_b32_e32 v26, 16, v27
	v_and_b32_e32 v27, 0xffff0000, v27
	v_lshlrev_b32_e32 v4, 16, v24
	v_and_b32_e32 v5, 0xffff0000, v24
	v_lshlrev_b32_e32 v6, 16, v25
	v_and_b32_e32 v7, 0xffff0000, v25
	s_addc_u32 s23, s11, 0
	v_lshlrev_b32_e32 v13, 2, v23
	v_lshl_add_u32 v14, v23, 4, 0
	s_mov_b64 s[24:25], 0
	v_mov_b32_e32 v15, v23
	s_branch .LBB0_1953
